# P2 epilogue: residual-base loads software-pipelined two row blocks ahead (3-slot register pool), counted vmcnt
# baseline (speedup 1.0000x reference)
; __device__ __forceinline__ unsigned cvt_pk_bf16(float lo, float hi) { f32x2_cv v = {lo, hi}; bf16x2_cv b = __builtin_convertvector(v, bf16x2_cv); return __builtin_bit_cast(unsigned, b); }
; __device__ __forceinline__ float bf_lo(unsigned w) { return __uint_as_float(w << 16); }
; __device__ __forceinline__ float bf_hi(unsigned w) { return __uint_as_float(w & 0xffff0000u); }
;     __device__ __forceinline__ void operator()(const f32x4 (&acc)[2][2][4][2], const Unit& u, int wr, int wc, int fr, int fq) const {
;         const float* base = (u.pm < split_pm) ? base0 + (size_t)u.pm * BM * 1024 : base1 + (size_t)(u.pm - split_pm) * BM * 1024;
;         const int lrow0 = wr * 64 + fr, col0 = u.pn * BM + wc * 32 + 8 * fq;
; #pragma unroll
;         for (int ai = 0; ai < 2; ++ai)
; #pragma unroll
;             for (int m = 0; m < 4; ++m) {
;                 int lrow = lrow0 + ai * HALF + m * 16; asm volatile("" : "+v"(lrow)); const size_t row = (size_t)u.pm * BM + lrow;
;                 float ss = 0.f;
; #pragma unroll
;                 for (int bj = 0; bj < 2; ++bj) {
;                     f32x4 b0, b1;
;                     if (baseb) { const u32x4 bw = *(const u32x4*)(baseb + row * 1024 + col0 + bj * HALF);
;                         b0 = (f32x4){bf_lo(bw.x), bf_hi(bw.x), bf_lo(bw.y), bf_hi(bw.y)}; b1 = (f32x4){bf_lo(bw.z), bf_hi(bw.z), bf_lo(bw.w), bf_hi(bw.w)}; }
;                     else { const float* bp = base + (size_t)lrow * 1024 + col0 + bj * HALF; b0 = *(const f32x4*)bp; b1 = *(const f32x4*)(bp + 4); }
;                     const f32x4 v0 = b0 + acc[ai][bj][m][0] * alpha, v1 = b1 + acc[ai][bj][m][1] * alpha;
;                     if (H) { float* hp = H + row * 1024 + col0 + bj * HALF; *(f32x4*)hp = v0; *(f32x4*)(hp + 4) = v1; }
;                     if (XN) { u32x4 w; w.x = cvt_pk_bf16(v0[0], v0[1]); w.y = cvt_pk_bf16(v0[2], v0[3]); w.z = cvt_pk_bf16(v1[0], v1[1]); w.w = cvt_pk_bf16(v1[2], v1[3]);
;                         *(u32x4*)(XN + row * 1024 + col0 + bj * HALF) = w; }
;                     ss += (v0[0] * v0[0] + v0[1] * v0[1]) + (v0[2] * v0[2] + v0[3] * v0[3]) + (v1[0] * v1[0] + v1[1] * v1[1]) + (v1[2] * v1[2] + v1[3] * v1[3]);
;                     asm volatile("" ::: "memory");
;                 }
;                 if (SS) { ss += __shfl_xor(ss, 16); ss += __shfl_xor(ss, 32); if (fq == 0) SS[row * 16 + u.pn * 4 + wc] = ss; }
.LBB0_265:
	v_lshl_or_b32 v146, s55, 8, v154
	v_mov_b32_e32 v150, v152
	v_ashrrev_i32_e32 v147, 31, v146
	v_lshl_add_u64 v[148:149], v[146:147], 2, s[34:35]
	v_lshlrev_b32_e32 v238, 12, v152
	v_mov_b32_e32 v239, 0
	v_lshl_add_u64 v[238:239], v[148:149], 0, v[238:239]
	global_load_dwordx4 v[202:205], v[238:239], off
	global_load_dwordx4 v[206:209], v[238:239], off offset:16
	global_load_dwordx4 v[210:213], v[238:239], off offset:512
	global_load_dwordx4 v[214:217], v[238:239], off offset:528
	v_lshlrev_b32_e32 v238, 12, v155
	v_mov_b32_e32 v239, 0
	v_lshl_add_u64 v[238:239], v[148:149], 0, v[238:239]
	global_load_dwordx4 v[218:221], v[238:239], off
	global_load_dwordx4 v[222:225], v[238:239], off offset:16
	global_load_dwordx4 v[226:229], v[238:239], off offset:512
	global_load_dwordx4 v[230:233], v[238:239], off offset:528
	v_lshlrev_b32_e32 v238, 12, v156
	v_mov_b32_e32 v239, 0
	v_lshl_add_u64 v[238:239], v[148:149], 0, v[238:239]
	global_load_dwordx4 v[182:185], v[238:239], off
	global_load_dwordx4 v[186:189], v[238:239], off offset:16
	global_load_dwordx4 v[190:193], v[238:239], off offset:512
	global_load_dwordx4 v[234:237], v[238:239], off offset:528
	v_ashrrev_i32_e32 v151, 31, v150
	s_lshl_b64 s[34:35], s[30:31], 8
	v_lshl_add_u64 v[150:151], s[34:35], 0, v[150:151]
	v_lshlrev_b64 v[176:177], 11, v[150:151]
	v_lshl_add_u64 v[176:177], s[20:21], 0, v[176:177]
	v_lshl_add_u64 v[176:177], v[146:147], 1, v[176:177]
	s_lshl_b32 s30, s55, 2
	s_ashr_i32 s31, s30, 31
	s_waitcnt vmcnt(8)
	v_pk_fma_f32 v[168:169], v[128:129], 0.5, v[204:205] op_sel_hi:[1,0,1]
	v_pk_fma_f32 v[166:167], v[126:127], 0.5, v[202:203] op_sel_hi:[1,0,1]
	v_pk_fma_f32 v[172:173], v[124:125], 0.5, v[208:209] op_sel_hi:[1,0,1]
	v_pk_fma_f32 v[170:171], v[122:123], 0.5, v[206:207] op_sel_hi:[1,0,1]
	v_cvt_pk_bf16_f32 v122, v166, v167
	v_cvt_pk_bf16_f32 v123, v168, v169
	v_cvt_pk_bf16_f32 v124, v170, v171
	v_cvt_pk_bf16_f32 v125, v172, v173
	global_store_dwordx4 v[176:177], v[122:125], off
	v_mul_f32_e32 v165, v167, v167
	v_mul_f32_e32 v167, v169, v169
	v_mul_f32_e32 v169, v171, v171
	v_fmac_f32_e32 v165, v166, v166
	v_fmac_f32_e32 v167, v168, v168
	v_mul_f32_e32 v171, v173, v173
	v_fmac_f32_e32 v169, v170, v170
	v_add_f32_e32 v165, v165, v167
	v_fmac_f32_e32 v171, v172, v172
	v_add_f32_e32 v165, v169, v165
	v_add_f32_e32 v165, v171, v165
	v_pk_fma_f32 v[120:121], v[120:121], 0.5, v[212:213] op_sel_hi:[1,0,1]
	v_pk_fma_f32 v[118:119], v[118:119], 0.5, v[210:211] op_sel_hi:[1,0,1]
	v_pk_fma_f32 v[122:123], v[116:117], 0.5, v[216:217] op_sel_hi:[1,0,1]
	v_pk_fma_f32 v[116:117], v[114:115], 0.5, v[214:215] op_sel_hi:[1,0,1]
	v_cvt_pk_bf16_f32 v114, v118, v119
	v_mul_f32_e32 v119, v119, v119
	v_mul_f32_e32 v125, v121, v121
	v_mul_f32_e32 v124, v117, v117
	v_fmac_f32_e32 v119, v118, v118
	v_fmac_f32_e32 v125, v120, v120
	v_mul_f32_e32 v115, v123, v123
	v_fmac_f32_e32 v124, v116, v116
	v_add_f32_e32 v118, v119, v125
	v_fmac_f32_e32 v115, v122, v122
	v_add_f32_e32 v118, v124, v118
	v_add_f32_e32 v115, v115, v118
	v_add_f32_e32 v118, v165, v115
	ds_bpermute_b32 v119, v199, v118
	v_cvt_pk_bf16_f32 v115, v120, v121
	v_cvt_pk_bf16_f32 v116, v116, v117
	v_cvt_pk_bf16_f32 v117, v122, v123
	global_store_dwordx4 v[176:177], v[114:117], off offset:256
	s_waitcnt lgkmcnt(0)
	s_nop 0
	v_add_f32_e32 v114, v118, v119
	ds_bpermute_b32 v115, v200, v114
	s_and_saveexec_b64 s[36:37], s[8:9]
	s_cbranch_execz .LBB0_267
	v_lshlrev_b64 v[116:117], 6, v[150:151]
	v_lshl_add_u64 v[116:117], s[22:23], 0, v[116:117]
	v_lshl_add_u64 v[116:117], s[30:31], 2, v[116:117]
	s_lshl_b32 s16, s47, 2
	v_lshl_add_u64 v[116:117], v[116:117], 0, s[16:17]
	s_waitcnt lgkmcnt(0)
	v_add_f32_e32 v114, v114, v115
	global_store_dword v[116:117], v114, off
.LBB0_267:
	s_or_b64 exec, exec, s[36:37]
	v_lshlrev_b32_e32 v238, 12, v157
	v_mov_b32_e32 v239, 0
	v_lshl_add_u64 v[238:239], v[148:149], 0, v[238:239]
	global_load_dwordx4 v[202:205], v[238:239], off
	global_load_dwordx4 v[206:209], v[238:239], off offset:16
	global_load_dwordx4 v[210:213], v[238:239], off offset:512
	global_load_dwordx4 v[214:217], v[238:239], off offset:528
	v_mov_b32_e32 v114, v155
	s_waitcnt lgkmcnt(0)
	v_ashrrev_i32_e32 v115, 31, v114
	v_lshl_add_u64 v[114:115], s[34:35], 0, v[114:115]
	v_lshlrev_b64 v[126:127], 11, v[114:115]
	v_lshl_add_u64 v[126:127], s[20:21], 0, v[126:127]
	v_lshl_add_u64 v[126:127], v[146:147], 1, v[126:127]
	s_waitcnt vmcnt(11)
	v_pk_fma_f32 v[118:119], v[112:113], 0.5, v[220:221] op_sel_hi:[1,0,1]
	v_pk_fma_f32 v[116:117], v[110:111], 0.5, v[218:219] op_sel_hi:[1,0,1]
	v_pk_fma_f32 v[122:123], v[108:109], 0.5, v[224:225] op_sel_hi:[1,0,1]
	v_pk_fma_f32 v[120:121], v[106:107], 0.5, v[222:223] op_sel_hi:[1,0,1]
	v_cvt_pk_bf16_f32 v106, v116, v117
	v_cvt_pk_bf16_f32 v107, v118, v119
	v_cvt_pk_bf16_f32 v108, v120, v121
	v_cvt_pk_bf16_f32 v109, v122, v123
	global_store_dwordx4 v[126:127], v[106:109], off
	v_mul_f32_e32 v117, v117, v117
	v_mul_f32_e32 v119, v119, v119
	v_mul_f32_e32 v121, v121, v121
	v_fmac_f32_e32 v117, v116, v116
	v_fmac_f32_e32 v119, v118, v118
	v_mul_f32_e32 v123, v123, v123
	v_fmac_f32_e32 v121, v120, v120
	v_add_f32_e32 v116, v117, v119
	v_fmac_f32_e32 v123, v122, v122
	v_add_f32_e32 v116, v121, v116
	v_add_f32_e32 v116, v123, v116
	v_pk_fma_f32 v[104:105], v[104:105], 0.5, v[228:229] op_sel_hi:[1,0,1]
	v_pk_fma_f32 v[102:103], v[102:103], 0.5, v[226:227] op_sel_hi:[1,0,1]
	v_pk_fma_f32 v[106:107], v[100:101], 0.5, v[232:233] op_sel_hi:[1,0,1]
	v_pk_fma_f32 v[100:101], v[98:99], 0.5, v[230:231] op_sel_hi:[1,0,1]
	v_cvt_pk_bf16_f32 v98, v102, v103
	v_mul_f32_e32 v103, v103, v103
	v_mul_f32_e32 v109, v105, v105
	v_mul_f32_e32 v108, v101, v101
	v_fmac_f32_e32 v103, v102, v102
	v_fmac_f32_e32 v109, v104, v104
	v_mul_f32_e32 v99, v107, v107
	v_fmac_f32_e32 v108, v100, v100
	v_add_f32_e32 v102, v103, v109
	v_fmac_f32_e32 v99, v106, v106
	v_add_f32_e32 v102, v108, v102
	v_add_f32_e32 v99, v99, v102
	v_add_f32_e32 v102, v116, v99
	ds_bpermute_b32 v103, v199, v102
	v_cvt_pk_bf16_f32 v99, v104, v105
	v_cvt_pk_bf16_f32 v100, v100, v101
	v_cvt_pk_bf16_f32 v101, v106, v107
	global_store_dwordx4 v[126:127], v[98:101], off offset:256
	s_waitcnt lgkmcnt(0)
	s_nop 0
	v_add_f32_e32 v98, v102, v103
	ds_bpermute_b32 v99, v200, v98
	s_and_saveexec_b64 s[36:37], s[8:9]
	s_cbranch_execz .LBB0_269
	v_lshlrev_b64 v[100:101], 6, v[114:115]
	v_lshl_add_u64 v[100:101], s[22:23], 0, v[100:101]
	v_lshl_add_u64 v[100:101], s[30:31], 2, v[100:101]
	s_lshl_b32 s16, s47, 2
	v_lshl_add_u64 v[100:101], v[100:101], 0, s[16:17]
	s_waitcnt lgkmcnt(0)
	v_add_f32_e32 v98, v98, v99
	global_store_dword v[100:101], v98, off
; __device__ __forceinline__ unsigned cvt_pk_bf16(float lo, float hi) { f32x2_cv v = {lo, hi}; bf16x2_cv b = __builtin_convertvector(v, bf16x2_cv); return __builtin_bit_cast(unsigned, b); }
; __device__ __forceinline__ float bf_lo(unsigned w) { return __uint_as_float(w << 16); }
; __device__ __forceinline__ float bf_hi(unsigned w) { return __uint_as_float(w & 0xffff0000u); }
;     __device__ __forceinline__ void operator()(const f32x4 (&acc)[2][2][4][2], const Unit& u, int wr, int wc, int fr, int fq) const {
;     ...
;             for (int m = 0; m < 4; ++m) {
;                 int lrow = lrow0 + ai * HALF + m * 16; asm volatile("" : "+v"(lrow)); const size_t row = (size_t)u.pm * BM + lrow;
;                 float ss = 0.f;
; #pragma unroll
;                 for (int bj = 0; bj < 2; ++bj) {
;                     f32x4 b0, b1;
;                     if (baseb) { const u32x4 bw = *(const u32x4*)(baseb + row * 1024 + col0 + bj * HALF);
;                         b0 = (f32x4){bf_lo(bw.x), bf_hi(bw.x), bf_lo(bw.y), bf_hi(bw.y)}; b1 = (f32x4){bf_lo(bw.z), bf_hi(bw.z), bf_lo(bw.w), bf_hi(bw.w)}; }
;                     else { const float* bp = base + (size_t)lrow * 1024 + col0 + bj * HALF; b0 = *(const f32x4*)bp; b1 = *(const f32x4*)(bp + 4); }
;                     const f32x4 v0 = b0 + acc[ai][bj][m][0] * alpha, v1 = b1 + acc[ai][bj][m][1] * alpha;
;                     if (H) { float* hp = H + row * 1024 + col0 + bj * HALF; *(f32x4*)hp = v0; *(f32x4*)(hp + 4) = v1; }
;                     if (XN) { u32x4 w; w.x = cvt_pk_bf16(v0[0], v0[1]); w.y = cvt_pk_bf16(v0[2], v0[3]); w.z = cvt_pk_bf16(v1[0], v1[1]); w.w = cvt_pk_bf16(v1[2], v1[3]);
;                         *(u32x4*)(XN + row * 1024 + col0 + bj * HALF) = w; }
;                     ss += (v0[0] * v0[0] + v0[1] * v0[1]) + (v0[2] * v0[2] + v0[3] * v0[3]) + (v1[0] * v1[0] + v1[1] * v1[1]) + (v1[2] * v1[2] + v1[3] * v1[3]);
;                     asm volatile("" ::: "memory");
;                 }
;                 if (SS) { ss += __shfl_xor(ss, 16); ss += __shfl_xor(ss, 32); if (fq == 0) SS[row * 16 + u.pn * 4 + wc] = ss; }
.LBB0_269:
	s_or_b64 exec, exec, s[36:37]
	v_lshlrev_b32_e32 v238, 12, v158
	v_mov_b32_e32 v239, 0
	v_lshl_add_u64 v[238:239], v[148:149], 0, v[238:239]
	global_load_dwordx4 v[218:221], v[238:239], off
	global_load_dwordx4 v[222:225], v[238:239], off offset:16
	global_load_dwordx4 v[226:229], v[238:239], off offset:512
	global_load_dwordx4 v[230:233], v[238:239], off offset:528
	v_mov_b32_e32 v98, v156
	s_waitcnt lgkmcnt(0)
	v_ashrrev_i32_e32 v99, 31, v98
	v_lshl_add_u64 v[98:99], s[34:35], 0, v[98:99]
	v_lshlrev_b64 v[110:111], 11, v[98:99]
	v_lshl_add_u64 v[110:111], s[20:21], 0, v[110:111]
	v_lshl_add_u64 v[110:111], v[146:147], 1, v[110:111]
	s_waitcnt vmcnt(14)
	v_pk_fma_f32 v[102:103], v[96:97], 0.5, v[184:185] op_sel_hi:[1,0,1]
	v_pk_fma_f32 v[100:101], v[94:95], 0.5, v[182:183] op_sel_hi:[1,0,1]
	v_pk_fma_f32 v[106:107], v[92:93], 0.5, v[188:189] op_sel_hi:[1,0,1]
	v_pk_fma_f32 v[104:105], v[90:91], 0.5, v[186:187] op_sel_hi:[1,0,1]
	v_cvt_pk_bf16_f32 v90, v100, v101
	v_cvt_pk_bf16_f32 v91, v102, v103
	v_cvt_pk_bf16_f32 v92, v104, v105
	v_cvt_pk_bf16_f32 v93, v106, v107
	global_store_dwordx4 v[110:111], v[90:93], off
	v_mul_f32_e32 v101, v101, v101
	v_mul_f32_e32 v103, v103, v103
	v_mul_f32_e32 v105, v105, v105
	v_fmac_f32_e32 v101, v100, v100
	v_fmac_f32_e32 v103, v102, v102
	v_mul_f32_e32 v107, v107, v107
	v_fmac_f32_e32 v105, v104, v104
	v_add_f32_e32 v100, v101, v103
	v_fmac_f32_e32 v107, v106, v106
	v_add_f32_e32 v100, v105, v100
	v_add_f32_e32 v100, v107, v100
	v_pk_fma_f32 v[88:89], v[88:89], 0.5, v[192:193] op_sel_hi:[1,0,1]
	v_pk_fma_f32 v[86:87], v[86:87], 0.5, v[190:191] op_sel_hi:[1,0,1]
	v_pk_fma_f32 v[90:91], v[84:85], 0.5, v[236:237] op_sel_hi:[1,0,1]
	v_pk_fma_f32 v[84:85], v[82:83], 0.5, v[234:235] op_sel_hi:[1,0,1]
	v_cvt_pk_bf16_f32 v82, v86, v87
	v_mul_f32_e32 v87, v87, v87
	v_mul_f32_e32 v93, v89, v89
	v_mul_f32_e32 v92, v85, v85
	v_fmac_f32_e32 v87, v86, v86
	v_fmac_f32_e32 v93, v88, v88
	v_mul_f32_e32 v83, v91, v91
	v_fmac_f32_e32 v92, v84, v84
	v_add_f32_e32 v86, v87, v93
	v_fmac_f32_e32 v83, v90, v90
	v_add_f32_e32 v86, v92, v86
	v_add_f32_e32 v83, v83, v86
	v_add_f32_e32 v86, v100, v83
	ds_bpermute_b32 v87, v199, v86
	v_cvt_pk_bf16_f32 v83, v88, v89
	v_cvt_pk_bf16_f32 v84, v84, v85
	v_cvt_pk_bf16_f32 v85, v90, v91
	global_store_dwordx4 v[110:111], v[82:85], off offset:256
	s_waitcnt lgkmcnt(0)
	s_nop 0
	v_add_f32_e32 v82, v86, v87
	ds_bpermute_b32 v83, v200, v82
	s_and_saveexec_b64 s[36:37], s[8:9]
	s_cbranch_execz .LBB0_271
	v_lshlrev_b64 v[84:85], 6, v[98:99]
	v_lshl_add_u64 v[84:85], s[22:23], 0, v[84:85]
	v_lshl_add_u64 v[84:85], s[30:31], 2, v[84:85]
	s_lshl_b32 s16, s47, 2
	v_lshl_add_u64 v[84:85], v[84:85], 0, s[16:17]
	s_waitcnt lgkmcnt(0)
	v_add_f32_e32 v82, v82, v83
	global_store_dword v[84:85], v82, off
.LBB0_271:
	s_or_b64 exec, exec, s[36:37]
	v_lshlrev_b32_e32 v238, 12, v159
	v_mov_b32_e32 v239, 0
	v_lshl_add_u64 v[238:239], v[148:149], 0, v[238:239]
	global_load_dwordx4 v[182:185], v[238:239], off
	global_load_dwordx4 v[186:189], v[238:239], off offset:16
	global_load_dwordx4 v[190:193], v[238:239], off offset:512
	global_load_dwordx4 v[234:237], v[238:239], off offset:528
	v_mov_b32_e32 v82, v157
	s_waitcnt lgkmcnt(0)
	v_ashrrev_i32_e32 v83, 31, v82
	v_lshl_add_u64 v[82:83], s[34:35], 0, v[82:83]
	v_lshlrev_b64 v[94:95], 11, v[82:83]
	v_lshl_add_u64 v[94:95], s[20:21], 0, v[94:95]
	v_lshl_add_u64 v[94:95], v[146:147], 1, v[94:95]
	s_waitcnt vmcnt(14)
	v_pk_fma_f32 v[86:87], v[80:81], 0.5, v[204:205] op_sel_hi:[1,0,1]
	v_pk_fma_f32 v[84:85], v[78:79], 0.5, v[202:203] op_sel_hi:[1,0,1]
	v_pk_fma_f32 v[90:91], v[76:77], 0.5, v[208:209] op_sel_hi:[1,0,1]
	v_pk_fma_f32 v[88:89], v[74:75], 0.5, v[206:207] op_sel_hi:[1,0,1]
	v_cvt_pk_bf16_f32 v74, v84, v85
	v_cvt_pk_bf16_f32 v75, v86, v87
	v_cvt_pk_bf16_f32 v76, v88, v89
	v_cvt_pk_bf16_f32 v77, v90, v91
	global_store_dwordx4 v[94:95], v[74:77], off
	v_mul_f32_e32 v85, v85, v85
	v_mul_f32_e32 v87, v87, v87
	v_mul_f32_e32 v89, v89, v89
	v_fmac_f32_e32 v85, v84, v84
	v_fmac_f32_e32 v87, v86, v86
	v_mul_f32_e32 v91, v91, v91
	v_fmac_f32_e32 v89, v88, v88
	v_add_f32_e32 v84, v85, v87
	v_fmac_f32_e32 v91, v90, v90
	v_add_f32_e32 v84, v89, v84
	v_add_f32_e32 v84, v91, v84
	v_pk_fma_f32 v[72:73], v[72:73], 0.5, v[212:213] op_sel_hi:[1,0,1]
	v_pk_fma_f32 v[70:71], v[70:71], 0.5, v[210:211] op_sel_hi:[1,0,1]
	v_pk_fma_f32 v[74:75], v[68:69], 0.5, v[216:217] op_sel_hi:[1,0,1]
	v_pk_fma_f32 v[68:69], v[66:67], 0.5, v[214:215] op_sel_hi:[1,0,1]
	v_cvt_pk_bf16_f32 v66, v70, v71
	v_mul_f32_e32 v71, v71, v71
	v_mul_f32_e32 v77, v73, v73
	v_mul_f32_e32 v76, v69, v69
	v_fmac_f32_e32 v71, v70, v70
	v_fmac_f32_e32 v77, v72, v72
	v_mul_f32_e32 v67, v75, v75
	v_fmac_f32_e32 v76, v68, v68
	v_add_f32_e32 v70, v71, v77
	v_fmac_f32_e32 v67, v74, v74
	v_add_f32_e32 v70, v76, v70
	v_add_f32_e32 v67, v67, v70
	v_add_f32_e32 v70, v84, v67
	ds_bpermute_b32 v71, v199, v70
	v_cvt_pk_bf16_f32 v67, v72, v73
	v_cvt_pk_bf16_f32 v68, v68, v69
	v_cvt_pk_bf16_f32 v69, v74, v75
	global_store_dwordx4 v[94:95], v[66:69], off offset:256
	s_waitcnt lgkmcnt(0)
	s_nop 0
	v_add_f32_e32 v66, v70, v71
	ds_bpermute_b32 v67, v200, v66
	s_and_saveexec_b64 s[36:37], s[8:9]
	s_cbranch_execz .LBB0_273
	v_lshlrev_b64 v[68:69], 6, v[82:83]
	v_lshl_add_u64 v[68:69], s[22:23], 0, v[68:69]
	v_lshl_add_u64 v[68:69], s[30:31], 2, v[68:69]
	s_lshl_b32 s16, s47, 2
	v_lshl_add_u64 v[68:69], v[68:69], 0, s[16:17]
	s_waitcnt lgkmcnt(0)
	v_add_f32_e32 v66, v66, v67
	global_store_dword v[68:69], v66, off
; __device__ __forceinline__ unsigned cvt_pk_bf16(float lo, float hi) { f32x2_cv v = {lo, hi}; bf16x2_cv b = __builtin_convertvector(v, bf16x2_cv); return __builtin_bit_cast(unsigned, b); }
; __device__ __forceinline__ float bf_lo(unsigned w) { return __uint_as_float(w << 16); }
; __device__ __forceinline__ float bf_hi(unsigned w) { return __uint_as_float(w & 0xffff0000u); }
;     __device__ __forceinline__ void operator()(const f32x4 (&acc)[2][2][4][2], const Unit& u, int wr, int wc, int fr, int fq) const {
;     ...
;             for (int m = 0; m < 4; ++m) {
;                 int lrow = lrow0 + ai * HALF + m * 16; asm volatile("" : "+v"(lrow)); const size_t row = (size_t)u.pm * BM + lrow;
;                 float ss = 0.f;
; #pragma unroll
;                 for (int bj = 0; bj < 2; ++bj) {
;                     f32x4 b0, b1;
;                     if (baseb) { const u32x4 bw = *(const u32x4*)(baseb + row * 1024 + col0 + bj * HALF);
;                         b0 = (f32x4){bf_lo(bw.x), bf_hi(bw.x), bf_lo(bw.y), bf_hi(bw.y)}; b1 = (f32x4){bf_lo(bw.z), bf_hi(bw.z), bf_lo(bw.w), bf_hi(bw.w)}; }
;                     else { const float* bp = base + (size_t)lrow * 1024 + col0 + bj * HALF; b0 = *(const f32x4*)bp; b1 = *(const f32x4*)(bp + 4); }
;                     const f32x4 v0 = b0 + acc[ai][bj][m][0] * alpha, v1 = b1 + acc[ai][bj][m][1] * alpha;
;                     if (H) { float* hp = H + row * 1024 + col0 + bj * HALF; *(f32x4*)hp = v0; *(f32x4*)(hp + 4) = v1; }
;                     if (XN) { u32x4 w; w.x = cvt_pk_bf16(v0[0], v0[1]); w.y = cvt_pk_bf16(v0[2], v0[3]); w.z = cvt_pk_bf16(v1[0], v1[1]); w.w = cvt_pk_bf16(v1[2], v1[3]);
;                         *(u32x4*)(XN + row * 1024 + col0 + bj * HALF) = w; }
;                     ss += (v0[0] * v0[0] + v0[1] * v0[1]) + (v0[2] * v0[2] + v0[3] * v0[3]) + (v1[0] * v1[0] + v1[1] * v1[1]) + (v1[2] * v1[2] + v1[3] * v1[3]);
;                     asm volatile("" ::: "memory");
;                 }
;                 if (SS) { ss += __shfl_xor(ss, 16); ss += __shfl_xor(ss, 32); if (fq == 0) SS[row * 16 + u.pn * 4 + wc] = ss; }
.LBB0_273:
	s_or_b64 exec, exec, s[36:37]
	v_lshlrev_b32_e32 v238, 12, v160
	v_mov_b32_e32 v239, 0
	v_lshl_add_u64 v[238:239], v[148:149], 0, v[238:239]
	global_load_dwordx4 v[202:205], v[238:239], off
	global_load_dwordx4 v[206:209], v[238:239], off offset:16
	global_load_dwordx4 v[210:213], v[238:239], off offset:512
	global_load_dwordx4 v[214:217], v[238:239], off offset:528
	v_mov_b32_e32 v66, v158
	s_waitcnt lgkmcnt(0)
	v_ashrrev_i32_e32 v67, 31, v66
	v_lshl_add_u64 v[66:67], s[34:35], 0, v[66:67]
	v_lshlrev_b64 v[78:79], 11, v[66:67]
	v_lshl_add_u64 v[78:79], s[20:21], 0, v[78:79]
	v_lshl_add_u64 v[78:79], v[146:147], 1, v[78:79]
	s_waitcnt vmcnt(14)
	v_pk_fma_f32 v[70:71], v[64:65], 0.5, v[220:221] op_sel_hi:[1,0,1]
	v_pk_fma_f32 v[68:69], v[62:63], 0.5, v[218:219] op_sel_hi:[1,0,1]
	v_pk_fma_f32 v[74:75], v[60:61], 0.5, v[224:225] op_sel_hi:[1,0,1]
	v_pk_fma_f32 v[72:73], v[58:59], 0.5, v[222:223] op_sel_hi:[1,0,1]
	v_cvt_pk_bf16_f32 v58, v68, v69
	v_cvt_pk_bf16_f32 v59, v70, v71
	v_cvt_pk_bf16_f32 v60, v72, v73
	v_cvt_pk_bf16_f32 v61, v74, v75
	global_store_dwordx4 v[78:79], v[58:61], off
	v_mul_f32_e32 v69, v69, v69
	v_mul_f32_e32 v71, v71, v71
	v_mul_f32_e32 v73, v73, v73
	v_fmac_f32_e32 v69, v68, v68
	v_fmac_f32_e32 v71, v70, v70
	v_mul_f32_e32 v75, v75, v75
	v_fmac_f32_e32 v73, v72, v72
	v_add_f32_e32 v68, v69, v71
	v_fmac_f32_e32 v75, v74, v74
	v_add_f32_e32 v68, v73, v68
	v_add_f32_e32 v68, v75, v68
	v_pk_fma_f32 v[56:57], v[56:57], 0.5, v[228:229] op_sel_hi:[1,0,1]
	v_pk_fma_f32 v[54:55], v[54:55], 0.5, v[226:227] op_sel_hi:[1,0,1]
	v_pk_fma_f32 v[58:59], v[52:53], 0.5, v[232:233] op_sel_hi:[1,0,1]
	v_pk_fma_f32 v[52:53], v[50:51], 0.5, v[230:231] op_sel_hi:[1,0,1]
	v_cvt_pk_bf16_f32 v50, v54, v55
	v_mul_f32_e32 v55, v55, v55
	v_mul_f32_e32 v61, v57, v57
	v_mul_f32_e32 v60, v53, v53
	v_fmac_f32_e32 v55, v54, v54
	v_fmac_f32_e32 v61, v56, v56
	v_mul_f32_e32 v51, v59, v59
	v_fmac_f32_e32 v60, v52, v52
	v_add_f32_e32 v54, v55, v61
	v_fmac_f32_e32 v51, v58, v58
	v_add_f32_e32 v54, v60, v54
	v_add_f32_e32 v51, v51, v54
	v_add_f32_e32 v54, v68, v51
	ds_bpermute_b32 v55, v199, v54
	v_cvt_pk_bf16_f32 v51, v56, v57
	v_cvt_pk_bf16_f32 v52, v52, v53
	v_cvt_pk_bf16_f32 v53, v58, v59
	global_store_dwordx4 v[78:79], v[50:53], off offset:256
	s_waitcnt lgkmcnt(0)
	s_nop 0
	v_add_f32_e32 v50, v54, v55
	ds_bpermute_b32 v51, v200, v50
	s_and_saveexec_b64 s[36:37], s[8:9]
	s_cbranch_execz .LBB0_275
	v_lshlrev_b64 v[52:53], 6, v[66:67]
	v_lshl_add_u64 v[52:53], s[22:23], 0, v[52:53]
	v_lshl_add_u64 v[52:53], s[30:31], 2, v[52:53]
	s_lshl_b32 s16, s47, 2
	v_lshl_add_u64 v[52:53], v[52:53], 0, s[16:17]
	s_waitcnt lgkmcnt(0)
	v_add_f32_e32 v50, v50, v51
	global_store_dword v[52:53], v50, off
.LBB0_275:
	s_or_b64 exec, exec, s[36:37]
	v_lshlrev_b32_e32 v238, 12, v161
	v_mov_b32_e32 v239, 0
	v_lshl_add_u64 v[238:239], v[148:149], 0, v[238:239]
	global_load_dwordx4 v[218:221], v[238:239], off
	global_load_dwordx4 v[222:225], v[238:239], off offset:16
	global_load_dwordx4 v[226:229], v[238:239], off offset:512
	global_load_dwordx4 v[230:233], v[238:239], off offset:528
	v_mov_b32_e32 v50, v159
	s_waitcnt lgkmcnt(0)
	v_ashrrev_i32_e32 v51, 31, v50
	v_lshl_add_u64 v[50:51], s[34:35], 0, v[50:51]
	v_lshlrev_b64 v[62:63], 11, v[50:51]
	v_lshl_add_u64 v[62:63], s[20:21], 0, v[62:63]
	v_lshl_add_u64 v[62:63], v[146:147], 1, v[62:63]
	s_waitcnt vmcnt(14)
	v_pk_fma_f32 v[54:55], v[48:49], 0.5, v[184:185] op_sel_hi:[1,0,1]
	v_pk_fma_f32 v[52:53], v[46:47], 0.5, v[182:183] op_sel_hi:[1,0,1]
	v_pk_fma_f32 v[58:59], v[44:45], 0.5, v[188:189] op_sel_hi:[1,0,1]
	v_pk_fma_f32 v[56:57], v[42:43], 0.5, v[186:187] op_sel_hi:[1,0,1]
	v_cvt_pk_bf16_f32 v42, v52, v53
	v_cvt_pk_bf16_f32 v43, v54, v55
	v_cvt_pk_bf16_f32 v44, v56, v57
	v_cvt_pk_bf16_f32 v45, v58, v59
	global_store_dwordx4 v[62:63], v[42:45], off
	v_mul_f32_e32 v53, v53, v53
	v_mul_f32_e32 v55, v55, v55
	v_mul_f32_e32 v57, v57, v57
	v_fmac_f32_e32 v53, v52, v52
	v_fmac_f32_e32 v55, v54, v54
	v_mul_f32_e32 v59, v59, v59
	v_fmac_f32_e32 v57, v56, v56
	v_add_f32_e32 v52, v53, v55
	v_fmac_f32_e32 v59, v58, v58
	v_add_f32_e32 v52, v57, v52
	v_add_f32_e32 v52, v59, v52
	v_pk_fma_f32 v[40:41], v[40:41], 0.5, v[192:193] op_sel_hi:[1,0,1]
	v_pk_fma_f32 v[38:39], v[38:39], 0.5, v[190:191] op_sel_hi:[1,0,1]
	v_pk_fma_f32 v[42:43], v[36:37], 0.5, v[236:237] op_sel_hi:[1,0,1]
	v_pk_fma_f32 v[36:37], v[34:35], 0.5, v[234:235] op_sel_hi:[1,0,1]
	v_cvt_pk_bf16_f32 v34, v38, v39
	v_mul_f32_e32 v39, v39, v39
	v_mul_f32_e32 v45, v41, v41
	v_mul_f32_e32 v44, v37, v37
	v_fmac_f32_e32 v39, v38, v38
	v_fmac_f32_e32 v45, v40, v40
	v_mul_f32_e32 v35, v43, v43
	v_fmac_f32_e32 v44, v36, v36
	v_add_f32_e32 v38, v39, v45
	v_fmac_f32_e32 v35, v42, v42
	v_add_f32_e32 v38, v44, v38
	v_add_f32_e32 v35, v35, v38
	v_add_f32_e32 v38, v52, v35
	ds_bpermute_b32 v39, v199, v38
	v_cvt_pk_bf16_f32 v35, v40, v41
	v_cvt_pk_bf16_f32 v36, v36, v37
	v_cvt_pk_bf16_f32 v37, v42, v43
	global_store_dwordx4 v[62:63], v[34:37], off offset:256
	s_waitcnt lgkmcnt(0)
	s_nop 0
	v_add_f32_e32 v34, v38, v39
	ds_bpermute_b32 v35, v200, v34
	s_and_saveexec_b64 s[36:37], s[8:9]
	s_cbranch_execz .LBB0_277
	v_lshlrev_b64 v[36:37], 6, v[50:51]
	v_lshl_add_u64 v[36:37], s[22:23], 0, v[36:37]
	v_lshl_add_u64 v[36:37], s[30:31], 2, v[36:37]
	s_lshl_b32 s16, s47, 2
	v_lshl_add_u64 v[36:37], v[36:37], 0, s[16:17]
	s_waitcnt lgkmcnt(0)
	v_add_f32_e32 v34, v34, v35
	global_store_dword v[36:37], v34, off
; __device__ __forceinline__ unsigned cvt_pk_bf16(float lo, float hi) { f32x2_cv v = {lo, hi}; bf16x2_cv b = __builtin_convertvector(v, bf16x2_cv); return __builtin_bit_cast(unsigned, b); }
; __device__ __forceinline__ float bf_lo(unsigned w) { return __uint_as_float(w << 16); }
; __device__ __forceinline__ float bf_hi(unsigned w) { return __uint_as_float(w & 0xffff0000u); }
;     __device__ __forceinline__ void operator()(const f32x4 (&acc)[2][2][4][2], const Unit& u, int wr, int wc, int fr, int fq) const {
;     ...
;             for (int m = 0; m < 4; ++m) {
;                 int lrow = lrow0 + ai * HALF + m * 16; asm volatile("" : "+v"(lrow)); const size_t row = (size_t)u.pm * BM + lrow;
;                 float ss = 0.f;
; #pragma unroll
;                 for (int bj = 0; bj < 2; ++bj) {
;                     f32x4 b0, b1;
;                     if (baseb) { const u32x4 bw = *(const u32x4*)(baseb + row * 1024 + col0 + bj * HALF);
;                         b0 = (f32x4){bf_lo(bw.x), bf_hi(bw.x), bf_lo(bw.y), bf_hi(bw.y)}; b1 = (f32x4){bf_lo(bw.z), bf_hi(bw.z), bf_lo(bw.w), bf_hi(bw.w)}; }
;                     else { const float* bp = base + (size_t)lrow * 1024 + col0 + bj * HALF; b0 = *(const f32x4*)bp; b1 = *(const f32x4*)(bp + 4); }
;                     const f32x4 v0 = b0 + acc[ai][bj][m][0] * alpha, v1 = b1 + acc[ai][bj][m][1] * alpha;
;                     if (H) { float* hp = H + row * 1024 + col0 + bj * HALF; *(f32x4*)hp = v0; *(f32x4*)(hp + 4) = v1; }
;                     if (XN) { u32x4 w; w.x = cvt_pk_bf16(v0[0], v0[1]); w.y = cvt_pk_bf16(v0[2], v0[3]); w.z = cvt_pk_bf16(v1[0], v1[1]); w.w = cvt_pk_bf16(v1[2], v1[3]);
;                         *(u32x4*)(XN + row * 1024 + col0 + bj * HALF) = w; }
;                     ss += (v0[0] * v0[0] + v0[1] * v0[1]) + (v0[2] * v0[2] + v0[3] * v0[3]) + (v1[0] * v1[0] + v1[1] * v1[1]) + (v1[2] * v1[2] + v1[3] * v1[3]);
;                     asm volatile("" ::: "memory");
;                 }
;                 if (SS) { ss += __shfl_xor(ss, 16); ss += __shfl_xor(ss, 32); if (fq == 0) SS[row * 16 + u.pn * 4 + wc] = ss; }
.LBB0_277:
	s_or_b64 exec, exec, s[36:37]
	v_mov_b32_e32 v34, v160
	s_waitcnt lgkmcnt(0)
	v_ashrrev_i32_e32 v35, 31, v34
	v_lshl_add_u64 v[34:35], s[34:35], 0, v[34:35]
	v_lshlrev_b64 v[46:47], 11, v[34:35]
	v_lshl_add_u64 v[46:47], s[20:21], 0, v[46:47]
	v_lshl_add_u64 v[46:47], v[146:147], 1, v[46:47]
	s_waitcnt vmcnt(10)
	v_pk_fma_f32 v[38:39], v[32:33], 0.5, v[204:205] op_sel_hi:[1,0,1]
	v_pk_fma_f32 v[36:37], v[30:31], 0.5, v[202:203] op_sel_hi:[1,0,1]
	v_pk_fma_f32 v[42:43], v[28:29], 0.5, v[208:209] op_sel_hi:[1,0,1]
	v_pk_fma_f32 v[40:41], v[26:27], 0.5, v[206:207] op_sel_hi:[1,0,1]
	v_cvt_pk_bf16_f32 v26, v36, v37
	v_cvt_pk_bf16_f32 v27, v38, v39
	v_cvt_pk_bf16_f32 v28, v40, v41
	v_cvt_pk_bf16_f32 v29, v42, v43
	global_store_dwordx4 v[46:47], v[26:29], off
	v_mul_f32_e32 v37, v37, v37
	v_mul_f32_e32 v39, v39, v39
	v_mul_f32_e32 v41, v41, v41
	v_fmac_f32_e32 v37, v36, v36
	v_fmac_f32_e32 v39, v38, v38
	v_mul_f32_e32 v43, v43, v43
	v_fmac_f32_e32 v41, v40, v40
	v_add_f32_e32 v36, v37, v39
	v_fmac_f32_e32 v43, v42, v42
	v_add_f32_e32 v36, v41, v36
	v_add_f32_e32 v36, v43, v36
	v_pk_fma_f32 v[24:25], v[24:25], 0.5, v[212:213] op_sel_hi:[1,0,1]
	v_pk_fma_f32 v[22:23], v[22:23], 0.5, v[210:211] op_sel_hi:[1,0,1]
	v_pk_fma_f32 v[26:27], v[20:21], 0.5, v[216:217] op_sel_hi:[1,0,1]
	v_pk_fma_f32 v[20:21], v[18:19], 0.5, v[214:215] op_sel_hi:[1,0,1]
	v_cvt_pk_bf16_f32 v18, v22, v23
	v_mul_f32_e32 v23, v23, v23
	v_mul_f32_e32 v29, v25, v25
	v_mul_f32_e32 v28, v21, v21
	v_fmac_f32_e32 v23, v22, v22
	v_fmac_f32_e32 v29, v24, v24
	v_mul_f32_e32 v19, v27, v27
	v_fmac_f32_e32 v28, v20, v20
	v_add_f32_e32 v22, v23, v29
	v_fmac_f32_e32 v19, v26, v26
	v_add_f32_e32 v22, v28, v22
	v_add_f32_e32 v19, v19, v22
	v_add_f32_e32 v22, v36, v19
	ds_bpermute_b32 v23, v199, v22
	v_cvt_pk_bf16_f32 v19, v24, v25
	v_cvt_pk_bf16_f32 v20, v20, v21
	v_cvt_pk_bf16_f32 v21, v26, v27
	global_store_dwordx4 v[46:47], v[18:21], off offset:256
	s_waitcnt lgkmcnt(0)
	s_nop 0
	v_add_f32_e32 v18, v22, v23
	ds_bpermute_b32 v19, v200, v18
	s_and_saveexec_b64 s[36:37], s[8:9]
	s_cbranch_execz .LBB0_279
	v_lshlrev_b64 v[20:21], 6, v[34:35]
	v_lshl_add_u64 v[20:21], s[22:23], 0, v[20:21]
	v_lshl_add_u64 v[20:21], s[30:31], 2, v[20:21]
	s_lshl_b32 s16, s47, 2
	v_lshl_add_u64 v[20:21], v[20:21], 0, s[16:17]
	s_waitcnt lgkmcnt(0)
	v_add_f32_e32 v18, v18, v19
	global_store_dword v[20:21], v18, off
.LBB0_279:
	s_or_b64 exec, exec, s[36:37]
	v_mov_b32_e32 v18, v161
	s_waitcnt lgkmcnt(0)
	v_ashrrev_i32_e32 v19, 31, v18
	v_lshl_add_u64 v[18:19], s[34:35], 0, v[18:19]
	v_lshlrev_b64 v[30:31], 11, v[18:19]
	v_lshl_add_u64 v[30:31], s[20:21], 0, v[30:31]
	v_lshl_add_u64 v[30:31], v[146:147], 1, v[30:31]
	s_waitcnt vmcnt(6)
	v_pk_fma_f32 v[22:23], v[16:17], 0.5, v[220:221] op_sel_hi:[1,0,1]
	v_pk_fma_f32 v[20:21], v[14:15], 0.5, v[218:219] op_sel_hi:[1,0,1]
	v_pk_fma_f32 v[26:27], v[12:13], 0.5, v[224:225] op_sel_hi:[1,0,1]
	v_pk_fma_f32 v[24:25], v[10:11], 0.5, v[222:223] op_sel_hi:[1,0,1]
	v_cvt_pk_bf16_f32 v10, v20, v21
	v_cvt_pk_bf16_f32 v11, v22, v23
	v_cvt_pk_bf16_f32 v12, v24, v25
	v_cvt_pk_bf16_f32 v13, v26, v27
	global_store_dwordx4 v[30:31], v[10:13], off
	v_mul_f32_e32 v21, v21, v21
	v_mul_f32_e32 v23, v23, v23
	v_mul_f32_e32 v25, v25, v25
	v_fmac_f32_e32 v21, v20, v20
	v_fmac_f32_e32 v23, v22, v22
	v_mul_f32_e32 v27, v27, v27
	v_fmac_f32_e32 v25, v24, v24
	v_add_f32_e32 v20, v21, v23
	v_fmac_f32_e32 v27, v26, v26
	v_add_f32_e32 v20, v25, v20
	v_add_f32_e32 v20, v27, v20
	v_pk_fma_f32 v[8:9], v[8:9], 0.5, v[228:229] op_sel_hi:[1,0,1]
	v_pk_fma_f32 v[6:7], v[6:7], 0.5, v[226:227] op_sel_hi:[1,0,1]
	v_pk_fma_f32 v[10:11], v[4:5], 0.5, v[232:233] op_sel_hi:[1,0,1]
	v_pk_fma_f32 v[4:5], v[2:3], 0.5, v[230:231] op_sel_hi:[1,0,1]
	v_cvt_pk_bf16_f32 v2, v6, v7
	v_mul_f32_e32 v7, v7, v7
	v_mul_f32_e32 v13, v9, v9
	v_mul_f32_e32 v12, v5, v5
	v_fmac_f32_e32 v7, v6, v6
	v_fmac_f32_e32 v13, v8, v8
	v_mul_f32_e32 v3, v11, v11
	v_fmac_f32_e32 v12, v4, v4
	v_add_f32_e32 v6, v7, v13
	v_fmac_f32_e32 v3, v10, v10
	v_add_f32_e32 v6, v12, v6
	v_add_f32_e32 v3, v3, v6
	v_add_f32_e32 v6, v20, v3
	ds_bpermute_b32 v7, v199, v6
	v_cvt_pk_bf16_f32 v3, v8, v9
	v_cvt_pk_bf16_f32 v4, v4, v5
	v_cvt_pk_bf16_f32 v5, v10, v11
	global_store_dwordx4 v[30:31], v[2:5], off offset:256
	s_waitcnt lgkmcnt(0)
	s_nop 0
	v_add_f32_e32 v2, v6, v7
	ds_bpermute_b32 v3, v200, v2
	s_and_saveexec_b64 s[34:35], s[8:9]
	s_cbranch_execz .LBB0_281
	v_lshlrev_b64 v[4:5], 6, v[18:19]
	v_lshl_add_u64 v[4:5], s[22:23], 0, v[4:5]
	v_lshl_add_u64 v[4:5], s[30:31], 2, v[4:5]
	s_lshl_b32 s16, s47, 2
	v_lshl_add_u64 v[4:5], v[4:5], 0, s[16:17]
	s_waitcnt lgkmcnt(0)
	v_add_f32_e32 v2, v2, v3
	global_store_dword v[4:5], v2, off
